# S5 step loop: out-projection stores deferred to the next step (stash in v116..v127) so the u-chunk wait does not cover fresh stores
# baseline (speedup 1.0000x reference)
; __device__ __forceinline__ unsigned f2bf(float f) { return pk2(f, f) & 0xffffu; }
; __device__ __forceinline__ float bf2f(unsigned short h) { return __uint_as_float(((unsigned)h) << 16); }
; __device__ __forceinline__ float gelu_tanh(float x) { const float u = 0.7978845608028654f * (x + 0.044715f * x * x * x); const float e = __expf(2.f * u); const float t = 1.f - 2.f * __builtin_amdgcn_rcpf(e + 1.f); return 0.5f * x * (1.f + t); }
; __device__ __forceinline__ void s5_unit(const Args& A, char* lds, int b, int g) {
;     ...
;             for (int r = 0; r < 4; ++r) { const size_t m = m0 + mt * 16 + 4 * fq + r; YD[m * 2048 + 1024 + g * 16 + fr] = (bf16)f2bf(gelu_tanh(acc[r] + dskip * bf2f(uv[r]))); } }
.LBB0_1345:
	s_cmp_lg_u32 s101, 0
	s_cbranch_scc0 .Ls5_nostb
	flat_store_short v[116:117], v124 offset:2048
	flat_store_short v[118:119], v125 offset:2048
	flat_store_short v[120:121], v126 offset:2048
	flat_store_short v[122:123], v127 offset:2048
	s_mov_b32 s101, 0

; __device__ __forceinline__ int opaque_tid() { int t = threadIdx.x; asm volatile("" : "+v"(t)); return t; }
; #define BAR_LDS() asm volatile("s_waitcnt lgkmcnt(0)\n\ts_barrier" ::: "memory")
; __device__ __forceinline__ void s5_unit(const Args& A, char* lds, int b, int g) {
;     const int tid = opaque_tid(), lane = tid & 63, wave = __builtin_amdgcn_readfirstlane(tid >> 6); const int fr = lane & 15, fq = lane >> 4, r32 = lane & 31, hi = lane >> 5;
;     const bf16* P1 = (const bf16*)(A.ws + WS_BIG); bf16* YD = (bf16*)A.out;
;     const unsigned char* pg = A.ws + WS_S5P + (size_t)g * S5P_STRIDE; const bf16* BbT = (const bf16*)pg; const bf16* Cm = (const bf16*)(pg + 4096); const float* ari = (const float*)(pg + 8192);
;     const int ttile = wave >> 2, ntile = wave & 3;
;     const bf16x8 bfrag = *(const bf16x8*)(BbT + (ntile * 32 + r32) * 16 + 8 * hi);
;     bf16x8 cfrag[4];
; #pragma unroll
;     for (int ks = 0; ks < 4; ++ks) cfrag[ks] = *(const bf16x8*)(Cm + fr * 128 + ks * 32 + 8 * fq);
;     const float ar = ari[lane], ai = ari[64 + lane]; float sr = 0.f, si = 0.f;
;     const float dskip = A.in[I_ODSKIP][g * 16 + fr];
;     const size_t rb0 = (size_t)b * SEQL; const bf16* pU = P1 + (rb0 + ttile * 32 + r32) * LD1 + C1_U + g * 16 + 8 * hi;
;     bf16x8 un = *(const bf16x8*)pU;
;     BAR_LDS();
.LBB0_1346:
	s_mov_b32 s101, 0
	s_and_b32 s8, s42, 31
	v_mov_b32_e32 v14, v220
	s_lshl_b32 s44, s8, 5
	s_and_b32 s8, s43, 31
	s_ashr_i32 s16, s43, 5
	v_readfirstlane_b32 s20, v14
	s_ashr_i32 s45, s20, 6
	s_mul_i32 s17, s8, 0x2200
	v_and_b32_e32 v48, 15, v14
	s_add_u32 s18, s4, s17
	s_addc_u32 s19, s5, 0
	v_lshlrev_b32_e32 v2, 8, v48
	v_mov_b32_e32 v3, v41
	v_and_b32_e32 v45, 31, v14
	v_lshl_add_u64 v[2:3], s[18:19], 0, v[2:3]
	v_and_b32_e32 v4, 48, v14
	v_mov_b32_e32 v5, v41
	v_and_b32_e32 v15, 63, v14
	s_and_b32 s21, s45, 3
	v_lshlrev_b32_e32 v0, 5, v45
	v_lshl_add_u64 v[2:3], v[2:3], 0, v[4:5]
	v_bfe_u32 v46, v14, 5, 1
	v_lshl_or_b32 v40, s21, 10, v0
	v_lshl_add_u64 v[6:7], v[2:3], 0, s[10:11]
	v_add_co_u32_e32 v2, vcc, s26, v2
	v_lshlrev_b32_e32 v8, 2, v15
	v_mov_b32_e32 v9, v41
	v_lshl_add_u64 v[0:1], s[18:19], 0, v[40:41]
	v_lshlrev_b32_e32 v40, 4, v46
	v_addc_co_u32_e32 v3, vcc, 0, v3, vcc
	v_lshl_add_u64 v[10:11], s[18:19], 0, v[8:9]
	s_ashr_i32 s18, s20, 3
	v_lshl_add_u64 v[0:1], v[0:1], 0, v[40:41]
	v_lshl_add_u64 v[12:13], v[10:11], 0, s[12:13]
	v_add_co_u32_e32 v10, vcc, s27, v10
	s_ashr_i32 s17, s16, 31
	s_and_b32 s46, s18, 0xffffffe0
	v_addc_co_u32_e32 v11, vcc, 0, v11, vcc
	flat_load_dwordx4 v[16:19], v[2:3]
	flat_load_dword v44, v[10:11]
	flat_load_dword v47, v[12:13] offset:256
	flat_load_dwordx4 v[20:23], v[0:1]
	flat_load_dwordx4 v[24:27], v[6:7] offset:64
	flat_load_dwordx4 v[28:31], v[6:7] offset:128
	flat_load_dwordx4 v[32:35], v[6:7] offset:192
	v_lshlrev_b32_e32 v0, 2, v48
	s_lshl_b64 s[22:23], s[16:17], 11
	s_ashr_i32 s16, s46, 31
	v_lshl_or_b32 v0, s8, 6, v0
	v_mov_b32_e32 v1, v41
	s_add_u32 s17, s22, s46
	v_lshl_add_u64 v[0:1], s[34:35], 0, v[0:1]
	v_or_b32_e32 v2, s17, v45
	flat_load_dword v57, v[0:1]
	s_addc_u32 s19, s23, s16
	v_mad_u64_u32 v[0:1], s[16:17], v2, s29, v[42:43]
	v_mad_i32_i24 v1, s19, v56, v1
	s_lshl_b32 s8, s8, 5
	v_lshl_add_u64 v[0:1], v[0:1], 0, s[8:9]
	v_lshl_add_u64 v[0:1], v[0:1], 0, v[40:41]
	v_add_co_u32_e32 v0, vcc, s30, v0
	s_mulk_i32 s19, 0x3800
	s_nop 0
	v_addc_co_u32_e32 v1, vcc, 0, v1, vcc
	flat_load_dwordx4 v[36:39], v[0:1] offset:3072
	v_mad_u64_u32 v[0:1], s[16:17], v2, s29, 0
	s_lshl_b32 s16, s21, 7
	s_add_i32 s47, s16, 0
	s_cmp_lt_u32 s20, 64
	s_cselect_b64 s[16:17], -1, 0
	s_cmp_gt_i32 s45, 3
	v_add_u32_e32 v1, s19, v1
	v_mov_b32_e32 v2, s18
	s_cselect_b64 s[18:19], -1, 0
	s_add_u32 s24, s1, s8
	s_addc_u32 s25, s0, 0
	s_cmp_eq_u32 s21, 0
	s_cselect_b64 s[20:21], -1, 0
	s_lshl_b32 s8, s45, 4
	v_bfi_b32 v58, s28, v2, v14
	s_sub_i32 s8, s8, 64
	v_lshrrev_b32_e32 v2, 2, v14
	v_and_b32_e32 v3, 12, v2
	v_or_b32_e32 v5, s8, v48
	v_or_b32_e32 v62, s8, v3
	v_mul_lo_u32 v5, v5, s36
	s_add_u32 s8, s22, s8
	s_waitcnt lgkmcnt(0)
	s_barrier
	v_lshl_or_b32 v7, v46, 2, s46
	v_lshlrev_b32_e32 v2, 1, v48
	v_add3_u32 v64, s33, v5, v4
	s_addc_u32 s22, s23, 0
	v_or_b32_e32 v4, s8, v3
	v_mov_b32_e32 v3, v41
	v_lshlrev_b32_e32 v6, 2, v45
	v_add_u32_e32 v63, s31, v2
	v_mov_b32_e32 v5, s22
	v_lshl_add_u64 v[48:49], s[24:25], 0, v[2:3]
	v_mul_lo_u32 v2, v7, s37
	v_or3_b32 v0, v0, s44, v40
	v_add_u32_e32 v59, s31, v40
	v_lshl_add_u32 v60, v15, 3, 0
	v_add_u32_e32 v61, s33, v8
	v_add3_u32 v65, s47, v6, v2
	v_lshlrev_b64 v[50:51], 12, v[4:5]
	v_lshl_add_u64 v[52:53], s[6:7], 0, v[0:1]
	s_movk_i32 s44, 0xff80
	s_mov_b32 s8, -2
	v_mov_b32_e32 v54, 0
	v_mov_b32_e32 v55, v41
	s_waitcnt vmcnt(0) lgkmcnt(0)
	v_mov_b32_e32 v45, v44
	v_xor_b32_e32 v46, 0x80000000, v47
	s_mov_b32 s99, s45
	v_mov_b32_e32 v136, v44
	v_mov_b32_e32 v137, v47
	v_mul_f32_e32 v138, v136, v44
	v_mul_f32_e32 v139, v136, v47
	v_fmac_f32_e32 v138, v137, v46
	v_fmac_f32_e32 v139, v137, v44
	v_mul_f32_e32 v140, v138, v44
	v_mul_f32_e32 v141, v138, v47
	v_fmac_f32_e32 v140, v139, v46
	v_fmac_f32_e32 v141, v139, v44
	v_mul_f32_e32 v142, v140, v44
	v_mul_f32_e32 v143, v140, v47
	v_fmac_f32_e32 v142, v141, v46
	v_fmac_f32_e32 v143, v141, v44
	v_mul_f32_e32 v144, v142, v44
	v_mul_f32_e32 v145, v142, v47
	v_fmac_f32_e32 v144, v143, v46
	v_fmac_f32_e32 v145, v143, v44
	v_mul_f32_e32 v146, v144, v44
	v_mul_f32_e32 v147, v144, v47
	v_fmac_f32_e32 v146, v145, v46
	v_fmac_f32_e32 v147, v145, v44
	v_mul_f32_e32 v148, v146, v44
	v_mul_f32_e32 v149, v146, v47
	v_fmac_f32_e32 v148, v147, v46
	v_fmac_f32_e32 v149, v147, v44
	v_mul_f32_e32 v150, v148, v44
	v_mul_f32_e32 v151, v148, v47
	v_fmac_f32_e32 v150, v149, v46
	v_fmac_f32_e32 v151, v149, v44
	v_mul_f32_e32 v152, v150, v44
	v_mul_f32_e32 v153, v150, v47
	v_fmac_f32_e32 v152, v151, v46
	v_fmac_f32_e32 v153, v151, v44
	v_mul_f32_e32 v154, v152, v44
	v_mul_f32_e32 v155, v152, v47
	v_fmac_f32_e32 v154, v153, v46
	v_fmac_f32_e32 v155, v153, v44
	v_mul_f32_e32 v156, v154, v44
	v_mul_f32_e32 v157, v154, v47
	v_fmac_f32_e32 v156, v155, v46
	v_fmac_f32_e32 v157, v155, v44
	v_mul_f32_e32 v158, v156, v44
	v_mul_f32_e32 v159, v156, v47
	v_fmac_f32_e32 v158, v157, v46
	v_fmac_f32_e32 v159, v157, v44
	v_mul_f32_e32 v160, v158, v44
	v_mul_f32_e32 v161, v158, v47
	v_fmac_f32_e32 v160, v159, v46
	v_fmac_f32_e32 v161, v159, v44
	v_mul_f32_e32 v162, v160, v44
	v_mul_f32_e32 v163, v160, v47
	v_fmac_f32_e32 v162, v161, v46
	v_fmac_f32_e32 v163, v161, v44
	v_mul_f32_e32 v164, v162, v44
	v_mul_f32_e32 v165, v162, v47
	v_fmac_f32_e32 v164, v163, v46
	v_fmac_f32_e32 v165, v163, v44
	v_mul_f32_e32 v166, v164, v44
	v_mul_f32_e32 v167, v164, v47
	v_fmac_f32_e32 v166, v165, v46
	v_fmac_f32_e32 v167, v165, v44
	s_lshl_b32 s100, s99, 9
	s_add_i32 s100, s100, 0x1b800
	v_add_u32_e32 v216, s100, v60
	v_add_u32_e32 v217, 0x1b800, v60
	s_branch .LBB0_1348

; __device__ __forceinline__ unsigned f2bf(float f) { return pk2(f, f) & 0xffffu; }
; __device__ __forceinline__ float bf2f(unsigned short h) { return __uint_as_float(((unsigned)h) << 16); }
; __device__ __forceinline__ float gelu_tanh(float x) { const float u = 0.7978845608028654f * (x + 0.044715f * x * x * x); const float e = __expf(2.f * u); const float t = 1.f - 2.f * __builtin_amdgcn_rcpf(e + 1.f); return 0.5f * x * (1.f + t); }
; __device__ __forceinline__ void s5_unit(const Args& A, char* lds, int b, int g) {
;     ...
;         if (wave >= 4 && i >= 2) { const bf16* SS = (const bf16*)(lds + S5_SS) + ((i - 2) & 1) * (64 * 136); const int mt = wave - 4; const size_t m0 = rb0 + (size_t)(i - 2) * 64;
;             unsigned short uv[4];
; #pragma unroll
;             for (int r = 0; r < 4; ++r) uv[r] = ((const bf16*)(lds + S5_US))[(((i - 2) & 3) * 64 + mt * 16 + 4 * fq + r) * 16 + fr];
;             f32x4m acc = (f32x4m){0.f, 0.f, 0.f, 0.f};
; #pragma unroll
;             for (int ks = 0; ks < 4; ++ks) { const bf16x8 af = *(const bf16x8*)(SS + (mt * 16 + fr) * 136 + ks * 32 + 8 * fq); acc = __builtin_amdgcn_mfma_f32_16x16x32_bf16(af, cfrag[ks], acc, 0, 0, 0); }
; #pragma unroll
;             for (int r = 0; r < 4; ++r) { const size_t m = m0 + mt * 16 + 4 * fq + r; YD[m * 2048 + 1024 + g * 16 + fr] = (bf16)f2bf(gelu_tanh(acc[r] + dskip * bf2f(uv[r]))); } }
.Ls5_nosta:
	s_cmp_gt_u32 s45, 1
	s_cselect_b64 s[22:23], -1, 0
	s_and_b64 s[22:23], s[18:19], s[22:23]
	s_andn2_b64 vcc, exec, s[22:23]
	s_cbranch_vccnz .LBB0_1347
	s_and_b32 s22, 1, s45
	s_and_b32 s23, s44, 0xc0
	s_cmp_eq_u32 s22, 1
	s_cselect_b32 s22, 0x4400, 0
	v_add_u32_e32 v12, s22, v64
	ds_read_b128 v[0:3], v12
	ds_read_b128 v[4:7], v12 offset:64
	v_add_u32_e32 v8, s23, v62
	v_lshl_add_u32 v40, v8, 5, v63
	ds_read_b128 v[8:11], v12 offset:128
	s_waitcnt lgkmcnt(0)
	v_mfma_f32_16x16x32_bf16 v[0:3], v[0:3], v[16:19], 0
	ds_read_b128 v[12:15], v12 offset:192
	s_lshl_b64 s[22:23], s[8:9], 18
	v_lshl_add_u64 v[66:67], s[22:23], 0, v[50:51]
	v_mfma_f32_16x16x32_bf16 v[0:3], v[4:7], v[24:27], v[0:3]
	ds_read_u16 v6, v40
	ds_read_u16 v7, v40 offset:32
	ds_read_u16 v68, v40 offset:64
	ds_read_u16 v40, v40 offset:96
	v_lshl_add_u64 v[4:5], v[48:49], 0, v[66:67]
	s_waitcnt lgkmcnt(0)
	v_lshlrev_b32_e32 v6, 16, v6
	v_mfma_f32_16x16x32_bf16 v[0:3], v[8:11], v[28:31], v[0:3]
	v_lshlrev_b32_e32 v7, 16, v7
	v_mfma_f32_16x16x32_bf16 v[0:3], v[12:15], v[32:35], v[0:3]
	s_nop 7
	v_fma_f32 v0, v57, v6, v0
	v_mul_f32_e32 v6, 0x3d372713, v0
	v_mul_f32_e32 v6, v0, v6
	v_fma_f32 v6, v0, v6, v0
	v_mul_f32_e32 v6, 0x3f4c422a, v6
	v_add_f32_e32 v6, v6, v6
	v_mul_f32_e32 v6, 0x3fb8aa3b, v6
	v_exp_f32_e32 v6, v6
	v_fma_f32 v1, v57, v7, v1
	v_mul_f32_e32 v7, 0x3d372713, v1
	v_mul_f32_e32 v7, v1, v7
	v_add_f32_e32 v6, 1.0, v6
	v_rcp_f32_e32 v6, v6
	v_fma_f32 v7, v1, v7, v1
	v_mul_f32_e32 v0, 0.5, v0
	v_mul_f32_e32 v7, 0x3f4c422a, v7
	v_fma_f32 v6, v6, -2.0, 1.0
	v_add_f32_e32 v6, 1.0, v6
	v_mul_f32_e32 v0, v0, v6
	v_add_f32_e32 v7, v7, v7
	v_cvt_pk_bf16_f32 v0, v0, s0
	v_mul_f32_e32 v7, 0x3fb8aa3b, v7
	v_mov_b32_e32 v116, v4
	v_mov_b32_e32 v117, v5
	v_mov_b32_e32 v124, v0
	v_lshlrev_b32_e32 v4, 16, v68
	v_exp_f32_e32 v7, v7
	v_fma_f32 v2, v57, v4, v2
	v_mul_f32_e32 v4, 0x3d372713, v2
	v_mul_f32_e32 v4, v2, v4
	v_fma_f32 v4, v2, v4, v2
	v_add_f32_e32 v7, 1.0, v7
	v_mul_f32_e32 v4, 0x3f4c422a, v4
	v_rcp_f32_e32 v7, v7
	v_add_f32_e32 v4, v4, v4
	v_mul_f32_e32 v4, 0x3fb8aa3b, v4
	v_exp_f32_e32 v4, v4
	v_fma_f32 v0, v7, -2.0, 1.0
	v_mul_f32_e32 v1, 0.5, v1
	v_add_f32_e32 v0, 1.0, v0
	v_mul_f32_e32 v0, v1, v0
	v_add_f32_e32 v1, 1.0, v4
	v_cvt_pk_bf16_f32 v5, v0, s0
	v_or_b32_e32 v0, 0x1000, v66
	v_rcp_f32_e32 v4, v1
	v_mov_b32_e32 v1, v67
	v_lshl_add_u64 v[0:1], v[48:49], 0, v[0:1]
	v_mov_b32_e32 v118, v0
	v_mov_b32_e32 v119, v1
	v_mov_b32_e32 v125, v5
	v_mul_f32_e32 v1, 0.5, v2
	v_lshlrev_b32_e32 v2, 16, v40
	v_fmac_f32_e32 v3, v57, v2
	v_mul_f32_e32 v2, 0x3d372713, v3
	v_mul_f32_e32 v2, v3, v2
	v_fma_f32 v2, v3, v2, v3
	v_mul_f32_e32 v2, 0x3f4c422a, v2
	v_add_f32_e32 v2, v2, v2
	v_mul_f32_e32 v2, 0x3fb8aa3b, v2
	v_exp_f32_e32 v2, v2
	v_fma_f32 v0, v4, -2.0, 1.0
	v_add_f32_e32 v0, 1.0, v0
	v_mul_f32_e32 v0, v1, v0
	v_add_f32_e32 v1, 1.0, v2
	v_rcp_f32_e32 v2, v1
	v_cvt_pk_bf16_f32 v4, v0, s0
	v_or_b32_e32 v0, 0x2000, v66
	v_mov_b32_e32 v1, v67
	v_lshl_add_u64 v[0:1], v[48:49], 0, v[0:1]
	v_mov_b32_e32 v120, v0
	v_mov_b32_e32 v121, v1
	v_mov_b32_e32 v126, v4
	v_fma_f32 v0, v2, -2.0, 1.0
	v_mul_f32_e32 v1, 0.5, v3
	v_add_f32_e32 v0, 1.0, v0
	v_mul_f32_e32 v0, v1, v0
	v_or_b32_e32 v66, 0x3000, v66
	v_cvt_pk_bf16_f32 v2, v0, s0
	v_lshl_add_u64 v[0:1], v[48:49], 0, v[66:67]
	v_mov_b32_e32 v122, v0
	v_mov_b32_e32 v123, v1
	v_mov_b32_e32 v127, v2
	s_mov_b32 s101, 1
	s_branch .LBB0_1347
